# attention prologue: bias-table staging ladder (8 x masked load / full wait / LDS write) de-serialised into 8 loads, one wait, 8 writes; on top of the P0 de-serialised best
# speedup vs baseline: 1.0027x; 1.0027x over previous
; DI void phase_attn(const Params& P, int l, LAS unsigned char* lds) {
;     ...
;     __syncthreads();
;     { const float* gt = (const float*)(P.ws + WS_TAB);
;       for (int i = tid; i < 8 * 512; i += NTHR) { const int h = i >> 9, idx = (i & 511) - 96; tab[i] = (idx >= 0 && idx <= 256) ? gt[h * 257 + idx] : -1e30f; } }
.LBB0_413:
	v_and_b32_e32 v2, 0x1ff, v137
	s_add_u32 s2, s50, 0x29e68000
	v_add_u32_e32 v2, 0xffffffa0, v2
	s_movk_i32 s4, 0x101
	s_addc_u32 s3, s51, 0
	v_cmp_gt_u32_e32 vcc, s4, v2
	v_readfirstlane_b32 s12, v137
	v_mov_b32_e32 v4, 0xf149f2ca
	v_mov_b32_e32 v5, 0xf149f2ca
	s_waitcnt vmcnt(0) lgkmcnt(0)
	s_barrier
	v_lshlrev_b32_e32 v3, 2, v2
	v_add_u32_e32 v6, 0x1010, v3
	v_mov_b32_e32 v8, 0xf149f2ca
	v_mov_b32_e32 v9, 0xf149f2ca
	v_mov_b32_e32 v10, 0xf149f2ca
	v_mov_b32_e32 v11, 0xf149f2ca
	v_mov_b32_e32 v12, 0xf149f2ca
	v_mov_b32_e32 v13, 0xf149f2ca
	v_mov_b32_e32 v14, 0xf149f2ca
	v_mov_b32_e32 v15, 0xf149f2ca
	s_and_saveexec_b64 s[0:1], vcc
	global_load_dword v8, v3, s[2:3]
	global_load_dword v9, v3, s[2:3] offset:1028
	global_load_dword v10, v3, s[2:3] offset:2056
	global_load_dword v11, v3, s[2:3] offset:3084
	global_load_dword v12, v6, s[2:3]
	global_load_dword v13, v6, s[2:3] offset:1028
	global_load_dword v14, v6, s[2:3] offset:2056
	global_load_dword v15, v6, s[2:3] offset:3084
	s_or_b64 exec, exec, s[0:1]
	v_lshl_add_u32 v7, v137, 2, 0
	v_add_u32_e32 v7, 0x20000, v7
	s_waitcnt vmcnt(0)
	ds_write_b32 v7, v8
	ds_write_b32 v7, v9 offset:2048
	ds_write_b32 v7, v10 offset:4096
	ds_write_b32 v7, v11 offset:6144
	ds_write_b32 v7, v12 offset:8192
	ds_write_b32 v7, v13 offset:10240
	ds_write_b32 v7, v14 offset:12288
	ds_write_b32 v7, v15 offset:14336
